# second row-scale table build: 32 partial-sum loads issued up front (was a two-deep load/wait chain)
# baseline (speedup 1.0000x reference)
; __device__ __forceinline__ int mk_ltid() { int t = threadIdx.x; asm volatile("" : "+v"(t)); return t; }
; #define LAS __attribute__((address_space(3)))
; __device__ __forceinline__ void rs_table(LAS float* RL, const float* SSP, int rbase) {
;     const int tid = mk_ltid();
; #pragma unroll
;     for (int i = 0; i < 4; ++i) { const int row = rbase + tid + 512 * i; float s = 0.f;
; #pragma unroll
;         for (int p = 0; p < 8; ++p) s += SSP[(size_t)p * MTOK + row];
;         RL[tid + 512 * i] = 1.0f / sqrtf(s * (1.f / DM) + RMS_EPS); }
.LBB0_810:
	s_or_b64 exec, exec, s[0:1]
	s_mov_b64 s[0:1], s[62:63]
	s_waitcnt lgkmcnt(0)
	s_barrier
	s_mov_b32 s4, s61
	s_load_dwordx2 s[0:1], s[0:1], 0xa0
	s_lshl_b32 s4, s4, 11
	s_and_b32 s4, s4, 0x3800
	v_mov_b32_e32 v0, v202
	v_mov_b32_e32 v40, 0x358637bd
	v_add_u32_e32 v2, s4, v0
	v_ashrrev_i32_e32 v3, 31, v2
	s_waitcnt lgkmcnt(0)
	v_lshl_add_u64 v[12:13], v[2:3], 2, s[0:1]
	v_lshlrev_b32_e32 v96, 2, v2
	v_add_u32_e32 v97, 0x1000, v96
	s_add_u32 s98, s0, 0x18600000
	s_addc_u32 s99, s1, 0
	global_load_dword v64, v96, s[98:99]
	global_load_dword v65, v96, s[98:99] offset:2048
	global_load_dword v66, v97, s[98:99]
	global_load_dword v67, v97, s[98:99] offset:2048
	s_add_u32 s98, s98, 0x10000
	s_addc_u32 s99, s99, 0
	global_load_dword v68, v96, s[98:99]
	global_load_dword v69, v96, s[98:99] offset:2048
	global_load_dword v70, v97, s[98:99]
	global_load_dword v71, v97, s[98:99] offset:2048
	s_add_u32 s98, s98, 0x10000
	s_addc_u32 s99, s99, 0
	global_load_dword v72, v96, s[98:99]
	global_load_dword v73, v96, s[98:99] offset:2048
	global_load_dword v74, v97, s[98:99]
	global_load_dword v75, v97, s[98:99] offset:2048
	s_add_u32 s98, s98, 0x10000
	s_addc_u32 s99, s99, 0
	global_load_dword v76, v96, s[98:99]
	global_load_dword v77, v96, s[98:99] offset:2048
	global_load_dword v78, v97, s[98:99]
	global_load_dword v79, v97, s[98:99] offset:2048
	s_add_u32 s98, s98, 0x10000
	s_addc_u32 s99, s99, 0
	global_load_dword v80, v96, s[98:99]
	global_load_dword v81, v96, s[98:99] offset:2048
	global_load_dword v82, v97, s[98:99]
	global_load_dword v83, v97, s[98:99] offset:2048
	s_add_u32 s98, s98, 0x10000
	s_addc_u32 s99, s99, 0
	global_load_dword v84, v96, s[98:99]
	global_load_dword v85, v96, s[98:99] offset:2048
	global_load_dword v86, v97, s[98:99]
	global_load_dword v87, v97, s[98:99] offset:2048
	s_add_u32 s98, s98, 0x10000
	s_addc_u32 s99, s99, 0
	global_load_dword v88, v96, s[98:99]
	global_load_dword v89, v96, s[98:99] offset:2048
	global_load_dword v90, v97, s[98:99]
	global_load_dword v91, v97, s[98:99] offset:2048
	s_add_u32 s98, s98, 0x10000
	s_addc_u32 s99, s99, 0
	global_load_dword v92, v96, s[98:99]
	global_load_dword v93, v96, s[98:99] offset:2048
	global_load_dword v94, v97, s[98:99]
	global_load_dword v95, v97, s[98:99] offset:2048
	s_mov_b64 s[0:1], 0x18600000
	v_lshl_add_u64 v[18:19], v[12:13], 0, s[0:1]
	s_mov_b32 s0, 0x18601000
	v_add_co_u32_e32 v16, vcc, s0, v12
	s_mov_b32 s0, 0x18610000
	s_nop 0
	v_addc_co_u32_e32 v17, vcc, 0, v13, vcc
	s_waitcnt vmcnt(0)
	v_mov_b32_e32 v2, v64
	v_add_co_u32_e32 v20, vcc, s0, v12
	s_mov_b32 s0, 0x18611000
	s_nop 0
	v_addc_co_u32_e32 v21, vcc, 0, v13, vcc
	s_mov_b32 s4, 0xf800000
	v_mov_b32_e32 v41, 0x260
	v_lshl_add_u32 v0, v0, 2, 0
	v_add_u32_e32 v0, 0x21000, v0
	s_lshl_b32 s24, s12, 25
	s_mov_b32 s25, s66
	s_mov_b32 s26, s61
	s_mov_b64 s[6:7], s[62:63]
	s_mov_b32 s13, s61
	v_mov_b32_e32 v18, v65
	s_waitcnt vmcnt(1)
	v_add_f32_e32 v4, 0, v2
	v_add_co_u32_e32 v2, vcc, s0, v12
	s_mov_b32 s0, 0x18620000
	s_nop 0
	v_addc_co_u32_e32 v3, vcc, 0, v13, vcc
	v_mov_b32_e32 v5, v68
	v_add_co_u32_e32 v22, vcc, s0, v12
	s_mov_b32 s0, 0x18621000
	s_nop 0
	v_addc_co_u32_e32 v23, vcc, 0, v13, vcc
	v_mov_b32_e32 v19, v69
	s_waitcnt vmcnt(2)
	v_add_f32_e32 v18, 0, v18
	s_waitcnt vmcnt(1)
	v_add_f32_e32 v6, v4, v5
	v_add_co_u32_e32 v4, vcc, s0, v12
	s_mov_b32 s0, 0x18630000
	s_nop 0
	v_addc_co_u32_e32 v5, vcc, 0, v13, vcc
	v_mov_b32_e32 v7, v72
	v_add_co_u32_e32 v24, vcc, s0, v12
	s_mov_b32 s0, 0x18631000
	s_nop 0
	v_addc_co_u32_e32 v25, vcc, 0, v13, vcc
	v_add_co_u32_e32 v8, vcc, s0, v12
	s_mov_b32 s0, 0x18640000
	s_nop 0
	v_addc_co_u32_e32 v9, vcc, 0, v13, vcc
	v_add_co_u32_e32 v26, vcc, s0, v12
	s_mov_b32 s0, 0x18641000
	s_nop 0
	v_addc_co_u32_e32 v27, vcc, 0, v13, vcc
	s_waitcnt vmcnt(1)
	v_add_f32_e32 v18, v18, v19
	v_mov_b32_e32 v19, v73
	s_waitcnt vmcnt(1)
	v_add_f32_e32 v6, v6, v7
	v_mov_b32_e32 v7, v76
	s_waitcnt vmcnt(1)
	v_add_f32_e32 v18, v18, v19
	v_mov_b32_e32 v19, v77
	s_waitcnt vmcnt(1)
	v_add_f32_e32 v10, v6, v7
	v_add_co_u32_e32 v6, vcc, s0, v12
	s_mov_b32 s0, 0x18650000
	s_nop 0
	v_addc_co_u32_e32 v7, vcc, 0, v13, vcc
	v_mov_b32_e32 v11, v80
	v_add_co_u32_e32 v28, vcc, s0, v12
	s_mov_b32 s0, 0x18651000
	s_nop 0
	v_addc_co_u32_e32 v29, vcc, 0, v13, vcc
	s_waitcnt vmcnt(1)
	v_add_f32_e32 v18, v18, v19
	v_mov_b32_e32 v19, v81
	s_waitcnt vmcnt(1)
	v_add_f32_e32 v14, v10, v11
	v_add_co_u32_e32 v10, vcc, s0, v12
	s_mov_b32 s0, 0x18660000
	s_nop 0
	v_addc_co_u32_e32 v11, vcc, 0, v13, vcc
	v_mov_b32_e32 v15, v84
	v_add_co_u32_e32 v30, vcc, s0, v12
	s_mov_b32 s0, 0x18661000
	s_nop 0
	v_addc_co_u32_e32 v31, vcc, 0, v13, vcc
	s_waitcnt vmcnt(1)
	v_add_f32_e32 v18, v18, v19
	v_mov_b32_e32 v19, v85
	s_waitcnt vmcnt(1)
	v_add_f32_e32 v32, v14, v15
	v_add_co_u32_e32 v14, vcc, s0, v12
	s_mov_b32 s0, 0x18670000
	s_nop 0
	v_addc_co_u32_e32 v15, vcc, 0, v13, vcc
	v_mov_b32_e32 v33, v88
	s_waitcnt vmcnt(1)
	v_add_f32_e32 v18, v18, v19
	v_mov_b32_e32 v19, v89
	s_waitcnt vmcnt(1)
	v_add_f32_e32 v34, v32, v33
	v_add_co_u32_e32 v32, vcc, s0, v12
	s_mov_b32 s0, 0x18671000
	s_nop 0
	v_addc_co_u32_e32 v33, vcc, 0, v13, vcc
	v_add_co_u32_e32 v12, vcc, s0, v12
	s_waitcnt vmcnt(0)
	v_add_f32_e32 v18, v18, v19
	v_addc_co_u32_e32 v13, vcc, 0, v13, vcc
	v_mov_b32_e32 v35, v92
	v_mov_b32_e32 v19, v93
	s_waitcnt vmcnt(1)
	v_add_f32_e32 v34, v34, v35
	v_fmamk_f32 v34, v34, 0x3a000000, v40
	v_cmp_gt_f32_e32 vcc, s4, v34
	v_mul_f32_e32 v35, 0x4f800000, v34
	s_waitcnt vmcnt(0)
; __device__ __forceinline__ int mk_ltid() { int t = threadIdx.x; asm volatile("" : "+v"(t)); return t; }
; #define LAS __attribute__((address_space(3)))
; __device__ __forceinline__ void rs_table(LAS float* RL, const float* SSP, int rbase) {
;     const int tid = mk_ltid();
; #pragma unroll
;     for (int i = 0; i < 4; ++i) { const int row = rbase + tid + 512 * i; float s = 0.f;
; #pragma unroll
;         for (int p = 0; p < 8; ++p) s += SSP[(size_t)p * MTOK + row];
;         RL[tid + 512 * i] = 1.0f / sqrtf(s * (1.f / DM) + RMS_EPS); }
;     __syncthreads();
; }
	v_add_f32_e32 v18, v18, v19
	v_cndmask_b32_e32 v34, v34, v35, vcc
	v_sqrt_f32_e32 v35, v34
	v_fmamk_f32 v18, v18, 0x3a000000, v40
	v_mul_f32_e32 v19, 0x4f800000, v18
	v_add_u32_e32 v36, -1, v35
	v_fma_f32 v37, -v36, v35, v34
	v_cmp_ge_f32_e64 s[0:1], 0, v37
	v_add_u32_e32 v37, 1, v35
	s_nop 0
	v_cndmask_b32_e64 v36, v35, v36, s[0:1]
	v_fma_f32 v35, -v37, v35, v34
	v_cmp_lt_f32_e64 s[0:1], 0, v35
	s_nop 1
	v_cndmask_b32_e64 v35, v36, v37, s[0:1]
	v_mul_f32_e32 v36, 0x37800000, v35
	v_cndmask_b32_e32 v35, v35, v36, vcc
	v_cmp_class_f32_e32 vcc, v34, v41
	s_nop 1
	v_cndmask_b32_e32 v34, v35, v34, vcc
	v_div_scale_f32 v35, s[0:1], v34, v34, 1.0
	v_rcp_f32_e32 v36, v35
	s_nop 0
	v_fma_f32 v37, -v35, v36, 1.0
	v_fmac_f32_e32 v36, v37, v36
	v_div_scale_f32 v37, vcc, 1.0, v34, 1.0
	v_mul_f32_e32 v38, v37, v36
	v_fma_f32 v39, -v35, v38, v37
	v_fmac_f32_e32 v38, v39, v36
	v_fma_f32 v35, -v35, v38, v37
	v_div_fmas_f32 v35, v35, v36, v38
	v_cmp_gt_f32_e32 vcc, s4, v18
	v_div_fixup_f32 v34, v35, v34, 1.0
	s_nop 0
	v_cndmask_b32_e32 v18, v18, v19, vcc
	v_sqrt_f32_e32 v19, v18
	s_nop 0
	v_add_u32_e32 v20, -1, v19
	v_fma_f32 v21, -v20, v19, v18
	v_cmp_ge_f32_e64 s[0:1], 0, v21
	v_add_u32_e32 v21, 1, v19
	s_nop 0
	v_cndmask_b32_e64 v20, v19, v20, s[0:1]
	v_fma_f32 v19, -v21, v19, v18
	v_cmp_lt_f32_e64 s[0:1], 0, v19
	s_nop 1
	v_cndmask_b32_e64 v19, v20, v21, s[0:1]
	v_mul_f32_e32 v20, 0x37800000, v19
	v_cndmask_b32_e32 v19, v19, v20, vcc
	v_cmp_class_f32_e32 vcc, v18, v41
	s_nop 1
	v_cndmask_b32_e32 v18, v19, v18, vcc
	v_div_scale_f32 v19, s[0:1], v18, v18, 1.0
	v_rcp_f32_e32 v20, v19
	s_nop 0
	v_fma_f32 v21, -v19, v20, 1.0
	v_fmac_f32_e32 v20, v21, v20
	v_div_scale_f32 v21, vcc, 1.0, v18, 1.0
	v_mul_f32_e32 v22, v21, v20
	v_fma_f32 v23, -v19, v22, v21
	v_fmac_f32_e32 v22, v23, v20
	v_fma_f32 v19, -v19, v22, v21
	v_div_fmas_f32 v19, v19, v20, v22
	v_div_fixup_f32 v18, v19, v18, 1.0
	ds_write2st64_b32 v0, v34, v18 offset1:8
	v_mov_b32_e32 v18, v66
	v_mov_b32_e32 v19, v70
	s_waitcnt vmcnt(1)
	v_add_f32_e32 v18, 0, v18
	s_waitcnt vmcnt(0)
	v_add_f32_e32 v18, v18, v19
	v_mov_b32_e32 v19, v74
	s_nop 0
	v_mov_b32_e32 v16, v67
	s_waitcnt vmcnt(0)
	v_add_f32_e32 v16, 0, v16
	v_mov_b32_e32 v2, v71
	v_add_f32_e32 v18, v18, v19
	v_mov_b32_e32 v19, v78
	v_mov_b32_e32 v3, v75
	s_waitcnt vmcnt(2)
	v_add_f32_e32 v2, v16, v2
	v_mov_b32_e32 v16, v202
	s_waitcnt vmcnt(1)
	v_add_f32_e32 v18, v18, v19
	v_mov_b32_e32 v19, v82
	s_waitcnt vmcnt(1)
	v_add_f32_e32 v2, v2, v3
	v_mov_b32_e32 v3, v79
	s_waitcnt vmcnt(1)
	v_add_f32_e32 v18, v18, v19
	v_mov_b32_e32 v19, v86
	s_waitcnt vmcnt(1)
	v_add_f32_e32 v2, v2, v3
	v_mov_b32_e32 v3, v83
	s_waitcnt vmcnt(1)
	v_add_f32_e32 v18, v18, v19
	v_mov_b32_e32 v19, v90
	s_waitcnt vmcnt(1)
	v_add_f32_e32 v2, v2, v3
	v_mov_b32_e32 v3, v87
	s_waitcnt vmcnt(1)
	v_add_f32_e32 v18, v18, v19
	v_mov_b32_e32 v19, v94
	s_waitcnt vmcnt(1)
	v_add_f32_e32 v2, v2, v3
	v_mov_b32_e32 v3, v91
	s_waitcnt vmcnt(1)
	v_add_f32_e32 v18, v18, v19
	v_fmamk_f32 v18, v18, 0x3a000000, v40
	v_cmp_gt_f32_e32 vcc, s4, v18
	v_mul_f32_e32 v19, 0x4f800000, v18
	s_waitcnt vmcnt(0)
	v_add_f32_e32 v2, v2, v3
	v_mov_b32_e32 v3, v95
	v_cndmask_b32_e32 v18, v18, v19, vcc
	v_sqrt_f32_e32 v19, v18
	s_waitcnt vmcnt(0)
	v_add_f32_e32 v2, v2, v3
	v_add_u32_e32 v20, -1, v19
	v_fma_f32 v21, -v20, v19, v18
	v_cmp_ge_f32_e64 s[0:1], 0, v21
	v_add_u32_e32 v21, 1, v19
	v_fmamk_f32 v2, v2, 0x3a000000, v40
	v_cndmask_b32_e64 v20, v19, v20, s[0:1]
	v_fma_f32 v19, -v21, v19, v18
	v_cmp_lt_f32_e64 s[0:1], 0, v19
	v_mul_f32_e32 v3, 0x4f800000, v2
	s_nop 0
	v_cndmask_b32_e64 v19, v20, v21, s[0:1]
	v_mul_f32_e32 v20, 0x37800000, v19
	v_cndmask_b32_e32 v19, v19, v20, vcc
	v_cmp_class_f32_e32 vcc, v18, v41
	s_nop 1
	v_cndmask_b32_e32 v18, v19, v18, vcc
	v_div_scale_f32 v19, s[0:1], v18, v18, 1.0
	v_rcp_f32_e32 v20, v19
	s_nop 0
	v_fma_f32 v21, -v19, v20, 1.0
	v_fmac_f32_e32 v20, v21, v20
	v_div_scale_f32 v21, vcc, 1.0, v18, 1.0
	v_mul_f32_e32 v22, v21, v20
	v_fma_f32 v23, -v19, v22, v21
	v_fmac_f32_e32 v22, v23, v20
	v_fma_f32 v19, -v19, v22, v21
	v_div_fmas_f32 v19, v19, v20, v22
	v_cmp_gt_f32_e32 vcc, s4, v2
	v_div_fixup_f32 v18, v19, v18, 1.0
	s_mov_b64 s[4:5], s[62:63]
	v_cndmask_b32_e32 v2, v2, v3, vcc
	v_sqrt_f32_e32 v3, v2
	s_nop 0
	v_add_u32_e32 v4, -1, v3
	v_fma_f32 v5, -v4, v3, v2
	v_cmp_ge_f32_e64 s[0:1], 0, v5
	v_add_u32_e32 v5, 1, v3
	s_nop 0
	v_cndmask_b32_e64 v4, v3, v4, s[0:1]
	v_fma_f32 v3, -v5, v3, v2
	v_cmp_lt_f32_e64 s[0:1], 0, v3
	s_nop 1
	v_cndmask_b32_e64 v3, v4, v5, s[0:1]
	v_mul_f32_e32 v4, 0x37800000, v3
	v_cndmask_b32_e32 v3, v3, v4, vcc
	v_cmp_class_f32_e32 vcc, v2, v41
	s_nop 1
	v_cndmask_b32_e32 v2, v3, v2, vcc
	v_div_scale_f32 v3, s[0:1], v2, v2, 1.0
	v_rcp_f32_e32 v4, v3
	s_mov_b64 s[0:1], s[62:63]
	v_fma_f32 v5, -v3, v4, 1.0
	v_fmac_f32_e32 v4, v5, v4
	v_div_scale_f32 v5, vcc, 1.0, v2, 1.0
	v_mul_f32_e32 v6, v5, v4
	v_fma_f32 v7, -v3, v6, v5
	v_fmac_f32_e32 v6, v7, v4
	v_fma_f32 v3, -v3, v6, v5
	v_div_fmas_f32 v3, v3, v4, v6
	v_div_fixup_f32 v2, v3, v2, 1.0
	ds_write2st64_b32 v0, v18, v2 offset0:16 offset1:24
	s_waitcnt lgkmcnt(0)
	s_barrier
	s_cmpk_gt_i32 s26, 0x7ff
	v_readfirstlane_b32 s12, v16
	s_cbranch_scc1 .LBB0_834
	s_ashr_i32 s27, s26, 31
	s_lshr_b32 s8, s27, 29
	s_add_i32 s16, s26, s8
	s_and_b32 s8, s16, -8
	s_sub_i32 s15, s26, s8
	s_cmp_gt_i32 s15, -1
	s_mov_b64 s[10:11], -1
	s_cbranch_scc0 .LBB0_813
	s_lshl_b32 s14, s15, 8
	s_mov_b64 s[10:11], 0

; __global__ void __launch_bounds__(512, 2) fwd_mega(Args a_unused) {
	.amdhsa_kernel _Z8fwd_mega4Args
		.amdhsa_group_segment_fixed_size 0
		.amdhsa_private_segment_fixed_size 0
		.amdhsa_kernarg_size 424
		.amdhsa_user_sgpr_count 2
		.amdhsa_user_sgpr_dispatch_ptr 0
		.amdhsa_user_sgpr_queue_ptr 0
		.amdhsa_user_sgpr_kernarg_segment_ptr 1
		.amdhsa_user_sgpr_dispatch_id 0
		.amdhsa_user_sgpr_kernarg_preload_length 0
		.amdhsa_user_sgpr_kernarg_preload_offset 0
		.amdhsa_user_sgpr_private_segment_size 0
		.amdhsa_uses_dynamic_stack 0
		.amdhsa_enable_private_segment 0
		.amdhsa_system_sgpr_workgroup_id_x 1
		.amdhsa_system_sgpr_workgroup_id_y 0
		.amdhsa_system_sgpr_workgroup_id_z 0
		.amdhsa_system_sgpr_workgroup_info 0
		.amdhsa_system_vgpr_workitem_id 2
		.amdhsa_next_free_vgpr 256
		.amdhsa_next_free_sgpr 102
		.amdhsa_accum_offset 256
		.amdhsa_reserve_vcc 1
		.amdhsa_float_round_mode_32 0
		.amdhsa_float_round_mode_16_64 0
		.amdhsa_float_denorm_mode_32 3
		.amdhsa_float_denorm_mode_16_64 3
		.amdhsa_dx10_clamp 1
		.amdhsa_ieee_mode 1
		.amdhsa_fp16_overflow 0
		.amdhsa_tg_split 0
		.amdhsa_exception_fp_ieee_invalid_op 0
		.amdhsa_exception_fp_denorm_src 0
		.amdhsa_exception_fp_ieee_div_zero 0
		.amdhsa_exception_fp_ieee_overflow 0
		.amdhsa_exception_fp_ieee_underflow 0
		.amdhsa_exception_fp_ieee_inexact 0
		.amdhsa_exception_int_div_zero 0
	.end_amdhsa_kernel

; __global__ void __launch_bounds__(512, 2) fwd_mega(Args a_unused) {
.Lfunc_end0:
	.size	_Z8fwd_mega4Args, .Lfunc_end0-_Z8fwd_mega4Args
	.set _Z8fwd_mega4Args.num_vgpr, 256
	.set _Z8fwd_mega4Args.num_agpr, 0
	.set _Z8fwd_mega4Args.numbered_sgpr, 102
	.set _Z8fwd_mega4Args.num_named_barrier, 0
	.set _Z8fwd_mega4Args.private_seg_size, 0
	.set _Z8fwd_mega4Args.uses_vcc, 1
	.set _Z8fwd_mega4Args.uses_flat_scratch, 0
	.set _Z8fwd_mega4Args.has_dyn_sized_stack, 0
	.set _Z8fwd_mega4Args.has_recursion, 0
	.set _Z8fwd_mega4Args.has_indirect_call, 0

; __global__ void __launch_bounds__(512, 2) fwd_mega(Args a_unused) {
amdhsa.kernels:
  - .agpr_count:     0
    .args:
      - .offset:         0
        .size:           168
        .value_kind:     by_value
      - .offset:         168
        .size:           4
        .value_kind:     hidden_block_count_x
      - .offset:         172
        .size:           4
        .value_kind:     hidden_block_count_y
      - .offset:         176
        .size:           4
        .value_kind:     hidden_block_count_z
      - .offset:         180
        .size:           2
        .value_kind:     hidden_group_size_x
      - .offset:         182
        .size:           2
        .value_kind:     hidden_group_size_y
      - .offset:         184
        .size:           2
        .value_kind:     hidden_group_size_z
      - .offset:         186
        .size:           2
        .value_kind:     hidden_remainder_x
      - .offset:         188
        .size:           2
        .value_kind:     hidden_remainder_y
      - .offset:         190
        .size:           2
        .value_kind:     hidden_remainder_z
      - .offset:         208
        .size:           8
        .value_kind:     hidden_global_offset_x
      - .offset:         216
        .size:           8
        .value_kind:     hidden_global_offset_y
      - .offset:         224
        .size:           8
        .value_kind:     hidden_global_offset_z
      - .offset:         232
        .size:           2
        .value_kind:     hidden_grid_dims
      - .offset:         256
        .size:           8
        .value_kind:     hidden_multigrid_sync_arg
      - .offset:         288
        .size:           4
        .value_kind:     hidden_dynamic_lds_size
    .group_segment_fixed_size: 0
    .kernarg_segment_align: 8
    .kernarg_segment_size: 424
    .language:       OpenCL C
    .language_version:
      - 2
      - 0
    .max_flat_workgroup_size: 512
    .name:           _Z8fwd_mega4Args
    .private_segment_fixed_size: 0
    .sgpr_count:     108
    .sgpr_spill_count: 104
    .symbol:         _Z8fwd_mega4Args.kd
    .uniform_work_group_size: 1
    .uses_dynamic_stack: false
    .vgpr_count:     256
    .vgpr_spill_count: 0
    .wavefront_size: 64
